# gate/up epilogue row-norm loads hoisted; NSA selected loop: next-tile column map + Q gather software-pipelined one tile ahead
# speedup vs baseline: 1.0208x; 1.0208x over previous
; #define GAS __attribute__((address_space(1)))
; #define LAS __attribute__((address_space(3)))
; __device__ __forceinline__ void nsa_phase(LAS unsigned char* lds, const bf16_t* Q, const bf16_t* KVG, size_t kvg_stride, const bf16_t* kcc, const bf16_t* vcc, const float* G, bf16_t* cat,
;                                           int tid, int lane, int wave) {
;     ...
; #pragma unroll
;                 for (int i = 0; i < 13; ++i) { const int e4 = lane_u + 64 * i; if (e4 < 816) *(LAS f32x4*)(Ssel + e4 * 4) = (f32x4){zs_, zs_, zs_, zs_}; }
;                 KVRegs R;
;                 __syncthreads();
;                 int tb = wave * 64 + lane_u; asm volatile("" : "+v"(tb));
;                 kv_fetch(R, gK + (size_t)nbeg * 4096, gV + (size_t)nbeg * 4096, tb, true);
;                 int kc_ = 0;
;                 const GAS bf16_t* Qw = (const GAS bf16_t*)(Qp + (size_t)(16 * wave) * 768);
;                 const unsigned w_own = selw[lr * 4 + q];
;                 for (int n = nbeg; n < nend; ++n) {
;                     LAS bf16_t* Kt = Kb0 + kc_ * 64 * 72; LAS bf16_t* Vt = Vb0 + kc_ * 64 * 72;
;                     kv_commit(R, Kt, Vt, tb, true);
;                     const bool bitn = ((w_own >> (n & 31)) & 1u) != 0u;
;                     const unsigned mask16 = (unsigned)((__builtin_amdgcn_ballot_w64(bitn) >> (16 * (n >> 5))) & 0xFFFFull);
;                     const int ksel = __builtin_popcount(mask16);
;                     const bool act = ((mask16 >> lr) & 1u) != 0u;
;                     if (act && q == 0) slist[__builtin_popcount(mask16 & ((1u << lr) - 1u))] = (unsigned)lr;
;                     asm volatile("s_waitcnt lgkmcnt(0)" ::: "memory");
;                     int jcg[3], rcg[3]; bool vg[3]; bf16x8 qB[3][2]; unsigned sl[3];
; #pragma unroll
;                     for (int gi = 0; gi < 3; ++gi) sl[gi] = slist[((16 * gi + lr) * 43) >> 7];
; #pragma unroll
;                     for (int gi = 0; gi < 3; ++gi) {
;                         const int cg = 16 * gi + lr, idx = (cg * 43) >> 7; rcg[gi] = cg - 3 * idx; vg[gi] = idx < ksel;
;                         jcg[gi] = vg[gi] ? (int)sl[gi] : 0;
;                         const GAS bf16_t* qg = Qw + (jcg[gi] * 768 + rcg[gi] * 64 + 8 * q);
;                         qB[gi][0] = *(const GAS bf16x8*)qg; qB[gi][1] = *(const GAS bf16x8*)(qg + 32);
;                     }
.LBB0_1040:
	s_or_b64 exec, exec, s[2:3]
	s_mov_b64 s[2:3], exec
	v_readlane_b32 s4, v255, 50
	v_readlane_b32 s5, v255, 51
	s_and_b64 s[4:5], s[2:3], s[4:5]
	s_mov_b64 exec, s[4:5]
	ds_write_b128 v215, v[24:27] offset:52224
	s_or_b64 exec, exec, s[2:3]
	s_mov_b64 s[2:3], exec
	v_readlane_b32 s4, v255, 52
	v_readlane_b32 s5, v255, 53
	s_and_b64 s[4:5], s[2:3], s[4:5]
	s_mov_b64 exec, s[4:5]
	ds_write_b128 v215, v[24:27] offset:53248
	s_or_b64 exec, exec, s[2:3]
	s_mov_b64 s[2:3], exec
	v_readlane_b32 s4, v255, 54
	v_readlane_b32 s5, v255, 55
	s_and_b64 s[4:5], s[2:3], s[4:5]
	s_mov_b64 exec, s[4:5]
	ds_write_b128 v215, v[24:27] offset:54272
	s_or_b64 exec, exec, s[2:3]
	s_mov_b64 s[2:3], exec
	v_readlane_b32 s4, v255, 56
	v_readlane_b32 s5, v255, 57
	s_and_b64 s[4:5], s[2:3], s[4:5]
	s_mov_b64 exec, s[4:5]
	ds_write_b128 v215, v[24:27] offset:55296
	s_or_b64 exec, exec, s[2:3]
	s_mov_b64 s[2:3], exec
	v_readlane_b32 s4, v255, 58
	v_readlane_b32 s5, v255, 59
	s_and_b64 s[4:5], s[2:3], s[4:5]
	s_mov_b64 exec, s[4:5]
	ds_write_b128 v215, v[24:27] offset:56320
	s_or_b64 exec, exec, s[2:3]
	s_mov_b64 s[2:3], exec
	v_readlane_b32 s4, v255, 60
	v_readlane_b32 s5, v255, 61
	s_and_b64 s[4:5], s[2:3], s[4:5]
	s_mov_b64 exec, s[4:5]
	ds_write_b128 v215, v[24:27] offset:57344
	s_or_b64 exec, exec, s[2:3]
	s_mov_b64 s[2:3], exec
	v_readlane_b32 s4, v255, 62
	v_readlane_b32 s5, v255, 63
	s_and_b64 s[4:5], s[2:3], s[4:5]
	s_mov_b64 exec, s[4:5]
	ds_write_b128 v215, v[24:27] offset:58368
	s_or_b64 exec, exec, s[2:3]
	v_mov_b32_e32 v33, v207
	s_cmp_lt_i32 s38, s43
	s_waitcnt lgkmcnt(0)
	s_barrier
	s_cbranch_scc0 .LBB0_948
	s_lshl_b64 s[2:3], s[38:39], 13
	s_add_u32 s4, s34, s2
	v_lshlrev_b32_e32 v34, 3, v33
	s_addc_u32 s5, s35, s3
	v_ashrrev_i32_e32 v35, 31, v34
	s_add_u32 s2, s10, s2
	v_lshlrev_b64 v[36:37], 1, v[34:35]
	s_addc_u32 s3, s11, s3
	v_lshl_add_u64 v[24:25], s[4:5], 0, v[36:37]
	v_lshl_add_u64 v[28:29], s[2:3], 0, v[36:37]
	global_load_dwordx4 v[24:27], v[24:25], off
	v_and_b32_e32 v87, 15, v32
	global_load_dwordx4 v[28:31], v[28:29], off
	v_ashrrev_i32_e32 v35, 4, v32
	v_and_b32_e32 v39, 56, v34
	v_cmp_gt_u32_e64 s[68:69], 16, v32
	v_and_b32_e32 v97, -16, v32
	v_bfe_u32 v34, v32, 2, 2
	v_lshlrev_b32_e32 v32, 2, v32
	v_and_b32_e32 v40, 12, v32
	v_mul_u32_u24_e32 v32, 43, v87
	v_lshlrev_b32_e32 v38, 4, v87
	v_lshlrev_b32_e32 v89, 2, v35
	v_readlane_b32 s2, v255, 37
	v_lshrrev_b32_e32 v105, 7, v32
	v_mad_u32_u24 v32, v87, 43, v223
	v_add3_u32 v38, s2, v38, v89
	v_lshrrev_b32_e32 v33, 3, v33
	s_movk_i32 s2, 0x48
	v_lshrrev_b32_e32 v106, 7, v32
	v_mad_u32_u24 v32, v87, 43, v224
	ds_read_b32 v91, v38
	v_mul_lo_u32 v38, v33, s2
	v_or_b32_e32 v34, v89, v34
	s_movk_i32 s2, 0x90
	v_lshrrev_b32_e32 v108, 7, v32
	v_mul_i32_i24_e32 v32, -3, v106
	v_mul_lo_u32 v104, v34, s2
	v_add3_u32 v92, v32, v87, 16
	v_mul_i32_i24_e32 v32, -3, v108
	v_readlane_b32 s2, v255, 43
	v_add3_u32 v96, v32, v87, 32
	v_lshlrev_b32_e64 v33, v87, -1
	v_sub_u32_e32 v32, s2, v89
	s_lshl_b32 s2, s38, 6
	v_subrev_u32_e32 v111, s2, v32
	s_ashr_i32 s3, s38, 31
	s_mov_b32 s2, s38
	v_not_b32_e32 v95, v33
	v_lshlrev_b32_e32 v33, 3, v35
	v_mad_i32_i24 v88, v105, -3, v87
	s_lshl_b64 s[2:3], s[2:3], 13
	v_lshl_add_u32 v90, v88, 6, v33
	v_lshl_add_u32 v94, v92, 6, v33
	v_lshl_add_u32 v98, v96, 6, v33
	v_lshl_add_u64 v[32:33], s[2:3], 0, v[36:37]
	v_lshl_add_u64 v[34:35], s[10:11], 0, v[32:33]
	v_lshl_add_u64 v[32:33], s[34:35], 0, v[32:33]
	v_lshlrev_b32_e64 v93, v87, 1
	v_mul_u32_u24_e32 v99, 0x90, v87
	v_lshl_add_u32 v107, v106, 2, s27
	v_lshl_add_u32 v109, v108, 2, s27
	v_lshl_add_u32 v110, v105, 2, s27
	v_lshl_add_u64 v[100:101], v[34:35], 0, s[22:23]
	v_lshl_add_u64 v[102:103], v[32:33], 0, s[22:23]
	s_mov_b32 s8, 0
	v_lshlrev_b32_e32 v112, 1, v38
	v_lshlrev_b32_e32 v113, 1, v39
	v_lshlrev_b32_e32 v114, 1, v40
	s_waitcnt lgkmcnt(0)
	s_and_b32 s2, s38, 31
	v_bfe_u32 v199, v91, s2, 1
	s_ashr_i32 s2, s38, 1
	v_cmp_ne_u32_e32 vcc, 0, v199
	s_and_b32 s2, s2, -16
	s_lshr_b64 s[2:3], vcc, s2
	v_and_b32_e32 v199, s2, v93
	v_cmp_ne_u32_e32 vcc, 0, v199
	s_and_b32 s4, s2, 0xffff
	s_bcnt1_i32_b32 s100, s4
	s_and_b64 vcc, vcc, s[68:69]
	s_and_saveexec_b64 s[4:5], vcc
	v_and_b32_e32 v199, s2, v95
	v_bcnt_u32_b32 v199, v199, 0
	v_lshl_add_u32 v199, v199, 2, s27
	ds_write_b32 v199, v87
	s_or_b64 exec, exec, s[4:5]
	s_cmp_eq_u32 s100, 0
	s_cbranch_scc1 .Lsp_gdone_pre
	s_waitcnt lgkmcnt(0)
	ds_read_b32 v200, v107
	ds_read_b32 v199, v109
	v_cmp_gt_u32_e64 s[4:5], s100, v105
	v_mov_b32_e32 v196, 0
	s_nop 0
	s_and_saveexec_b64 s[2:3], s[4:5]
	ds_read_b32 v196, v110
	s_or_b64 exec, exec, s[2:3]
	s_waitcnt lgkmcnt(0)
	v_mad_u64_u32 v[202:203], s[2:3], v196, s48, v[90:91]
	v_ashrrev_i32_e32 v203, 31, v202
	v_cmp_gt_u32_e64 s[4:5], s100, v106
	v_cmp_gt_u32_e64 vcc, s100, v108
	v_lshl_add_u64 v[202:203], v[202:203], 1, s[30:31]
	s_nop 0
	v_cndmask_b32_e64 v197, 0, v200, s[4:5]
	v_cndmask_b32_e64 v198, 0, v199, vcc
	global_load_dwordx4 v[228:231], v[202:203], off
	global_load_dwordx4 v[232:235], v[202:203], off offset:64
	s_cmp_lt_u32 s100, 6
	s_cbranch_scc1 .Lsp_gdone_pre
	v_mad_u64_u32 v[202:203], s[2:3], v197, s48, v[94:95]
	v_ashrrev_i32_e32 v203, 31, v202
	v_lshl_add_u64 v[202:203], v[202:203], 1, s[30:31]
	global_load_dwordx4 v[236:239], v[202:203], off
	global_load_dwordx4 v[240:243], v[202:203], off offset:64
	s_cmp_lt_u32 s100, 11
	s_cbranch_scc1 .Lsp_gdone_pre
	v_mad_u64_u32 v[216:217], s[2:3], v198, s48, v[98:99]
	v_ashrrev_i32_e32 v217, 31, v216
	v_lshl_add_u64 v[216:217], v[216:217], 1, s[30:31]
	global_load_dwordx4 v[244:247], v[216:217], off
	global_load_dwordx4 v[248:251], v[216:217], off offset:64
.Lsp_gdone_pre:
	s_branch .LBB0_1058

; #define GAS __attribute__((address_space(1)))
; #define LAS __attribute__((address_space(3)))
; __device__ __forceinline__ void nsa_phase(LAS unsigned char* lds, const bf16_t* Q, const bf16_t* KVG, size_t kvg_stride, const bf16_t* kcc, const bf16_t* vcc, const float* G, bf16_t* cat,
;                                           int tid, int lane, int wave) {
;     ...
;                 for (int n = nbeg; n < nend; ++n) {
;                     LAS bf16_t* Kt = Kb0 + kc_ * 64 * 72; LAS bf16_t* Vt = Vb0 + kc_ * 64 * 72;
;                     kv_commit(R, Kt, Vt, tb, true);
;                     const bool bitn = ((w_own >> (n & 31)) & 1u) != 0u;
;                     const unsigned mask16 = (unsigned)((__builtin_amdgcn_ballot_w64(bitn) >> (16 * (n >> 5))) & 0xFFFFull);
;                     const int ksel = __builtin_popcount(mask16);
;                     const bool act = ((mask16 >> lr) & 1u) != 0u;
;                     if (act && q == 0) slist[__builtin_popcount(mask16 & ((1u << lr) - 1u))] = (unsigned)lr;
;                     asm volatile("s_waitcnt lgkmcnt(0)" ::: "memory");
;                     int jcg[3], rcg[3]; bool vg[3]; bf16x8 qB[3][2]; unsigned sl[3];
; #pragma unroll
;                     for (int gi = 0; gi < 3; ++gi) sl[gi] = slist[((16 * gi + lr) * 43) >> 7];
; #pragma unroll
;                     for (int gi = 0; gi < 3; ++gi) {
;                         const int cg = 16 * gi + lr, idx = (cg * 43) >> 7; rcg[gi] = cg - 3 * idx; vg[gi] = idx < ksel;
;                         jcg[gi] = vg[gi] ? (int)sl[gi] : 0;
;                         const GAS bf16_t* qg = Qw + (jcg[gi] * 768 + rcg[gi] * 64 + 8 * q);
;                         qB[gi][0] = *(const GAS bf16x8*)qg; qB[gi][1] = *(const GAS bf16x8*)(qg + 32);
;                     }
;                     if (n + 1 < nend) kv_fetch(R, gK + (size_t)(n + 1) * 4096, gV + (size_t)(n + 1) * 4096, tb, true);
;                     __syncthreads();
;                     const int ng = (3 * ksel + 15) >> 4;
;                     const bool msk = (n == ((t0 + 16 * wave) >> 6));
; #pragma unroll
;                     for (int gi = 0; gi < 3; ++gi)
;                         if (gi < ng) sel_group(Kt, Vt, Ssel, qB[gi][0], qB[gi][1], jcg[gi], rcg[gi], vg[gi], msk, t0 + 16 * wave - 64 * n, lr, q);
.LBB0_1058:
	s_mul_i32 s2, s8, 0x2400
	s_add_i32 s6, s2, 0
	s_mov_b32 s10, s100
	s_waitcnt vmcnt(0)
	v_add3_u32 v32, s6, v112, v113
	ds_write_b128 v32, v[28:31]
	ds_write_b128 v32, v[24:27] offset:18432
	s_add_i32 s9, s38, 1
	s_cmp_ge_i32 s9, s43
	s_cselect_b32 s101, 1, 0
	s_cbranch_scc1 .Lsp_movs
	s_and_b32 s2, s9, 31
	v_bfe_u32 v199, v91, s2, 1
	s_ashr_i32 s2, s9, 1
	v_cmp_ne_u32_e32 vcc, 0, v199
	s_and_b32 s2, s2, -16
	s_lshr_b64 s[2:3], vcc, s2
	v_and_b32_e32 v199, s2, v93
	v_cmp_ne_u32_e32 vcc, 0, v199
	s_and_b32 s4, s2, 0xffff
	s_bcnt1_i32_b32 s100, s4
	s_and_b64 vcc, vcc, s[68:69]
	s_and_saveexec_b64 s[4:5], vcc
	v_and_b32_e32 v199, s2, v95
	v_bcnt_u32_b32 v199, v199, 0
	v_lshl_add_u32 v199, v199, 2, s27
	ds_write_b32 v199, v87
	s_or_b64 exec, exec, s[4:5]
	global_load_dwordx4 v[28:31], v[100:101], off
	global_load_dwordx4 v[24:27], v[102:103], off
.Lsp_movs:
	v_mov_b32_e32 v120, v196
	v_mov_b32_e32 v118, v197
	v_mov_b32_e32 v116, v198
	v_mov_b64_e32 v[76:77], v[228:229]
	v_mov_b64_e32 v[78:79], v[230:231]
	v_mov_b64_e32 v[80:81], v[232:233]
	v_mov_b64_e32 v[82:83], v[234:235]
	v_mov_b64_e32 v[40:41], v[236:237]
	v_mov_b64_e32 v[42:43], v[238:239]
	v_mov_b64_e32 v[44:45], v[240:241]
	v_mov_b64_e32 v[46:47], v[242:243]
	v_mov_b64_e32 v[32:33], v[244:245]
	v_mov_b64_e32 v[34:35], v[246:247]
	v_mov_b64_e32 v[36:37], v[248:249]
	v_mov_b64_e32 v[38:39], v[250:251]
	v_cmp_gt_u32_e64 s[76:77], s10, v105
	v_cmp_gt_u32_e64 s[74:75], s10, v106
	v_cmp_gt_u32_e64 s[70:71], s10, v108
	s_cmp_eq_u32 s101, 1
	s_cbranch_scc1 .Lsp_gdone_loop
	s_cmp_eq_u32 s100, 0
	s_cbranch_scc1 .Lsp_gdone_loop
	s_waitcnt lgkmcnt(0)
	ds_read_b32 v200, v107
	ds_read_b32 v199, v109
	v_cmp_gt_u32_e64 s[4:5], s100, v105
	v_mov_b32_e32 v196, 0
	s_nop 0
	s_and_saveexec_b64 s[2:3], s[4:5]
	ds_read_b32 v196, v110
	s_or_b64 exec, exec, s[2:3]
	s_waitcnt lgkmcnt(0)
	v_mad_u64_u32 v[202:203], s[2:3], v196, s48, v[90:91]
	v_ashrrev_i32_e32 v203, 31, v202
	v_cmp_gt_u32_e64 s[4:5], s100, v106
	v_cmp_gt_u32_e64 vcc, s100, v108
	v_lshl_add_u64 v[202:203], v[202:203], 1, s[30:31]
	s_nop 0
	v_cndmask_b32_e64 v197, 0, v200, s[4:5]
	v_cndmask_b32_e64 v198, 0, v199, vcc
	global_load_dwordx4 v[228:231], v[202:203], off
	global_load_dwordx4 v[232:235], v[202:203], off offset:64
	s_cmp_lt_u32 s100, 6
	s_cbranch_scc1 .Lsp_gdone_loop
	v_mad_u64_u32 v[202:203], s[2:3], v197, s48, v[94:95]
	v_ashrrev_i32_e32 v203, 31, v202
	v_lshl_add_u64 v[202:203], v[202:203], 1, s[30:31]
	global_load_dwordx4 v[236:239], v[202:203], off
	global_load_dwordx4 v[240:243], v[202:203], off offset:64
	s_cmp_lt_u32 s100, 11
	s_cbranch_scc1 .Lsp_gdone_loop
	v_mad_u64_u32 v[216:217], s[2:3], v198, s48, v[98:99]
	v_ashrrev_i32_e32 v217, 31, v216
	v_lshl_add_u64 v[216:217], v[216:217], 1, s[30:31]
	global_load_dwordx4 v[244:247], v[216:217], off
	global_load_dwordx4 v[248:251], v[216:217], off offset:64
.Lsp_gdone_loop:
	s_waitcnt lgkmcnt(0)
	s_cmp_eq_u32 s101, 1
	s_cselect_b64 s[2:3], -1, 0
	s_cmp_eq_u32 s45, s38
	s_cselect_b64 s[12:13], -1, 0
	v_add_u32_e32 v48, s6, v99
	v_add_u32_e32 v117, v48, v97
	v_cndmask_b32_e64 v48, 0, 1, s[12:13]
	v_add3_u32 v115, s6, v104, v114
	s_cmp_eq_u32 s10, 0
	v_cmp_ne_u32_e64 s[72:73], 1, v48
	s_barrier
	s_cbranch_scc1 .LBB0_1078
	v_mad_u64_u32 v[48:49], s[4:5], v120, 3, v[88:89]
	v_mul_lo_u32 v48, v48, s36
	v_add_u32_e32 v119, s49, v48
	v_add_u32_e32 v48, v119, v97
	ds_read_b96 v[84:86], v119 offset:46336
	ds_read_b128 v[60:63], v48 offset:46080
	ds_read_b128 v[56:59], v48 offset:46144
	ds_read_b128 v[52:55], v48 offset:46208
	ds_read_b128 v[48:51], v48 offset:46272
	ds_read_b128 v[64:67], v117
	ds_read_b128 v[68:71], v117 offset:64
	ds_read_b128 v[72:75], v117 offset:2304
	ds_read_b128 v[122:125], v117 offset:2368
	s_waitcnt lgkmcnt(8)
	v_cndmask_b32_e64 v126, v222, -v85, s[76:77]
	v_mov_b32_e32 v127, v126
	v_mov_b32_e32 v128, v126
	v_mov_b32_e32 v129, v126
	s_setprio 1
	s_waitcnt lgkmcnt(3)
	v_mfma_f32_16x16x32_bf16 v[64:67], v[64:67], v[76:79], v[126:129]
	s_waitcnt lgkmcnt(2)
	v_mfma_f32_16x16x32_bf16 v[64:67], v[68:71], v[80:83], v[64:67]
	s_setprio 0
	ds_read_b128 v[130:133], v117 offset:4608
	ds_read_b128 v[134:137], v117 offset:4672
	s_setprio 1
	s_waitcnt lgkmcnt(3)
	v_mfma_f32_16x16x32_bf16 v[68:71], v[72:75], v[76:79], v[126:129]
	s_waitcnt lgkmcnt(2)
	v_mfma_f32_16x16x32_bf16 v[68:71], v[122:125], v[80:83], v[68:71]
	s_setprio 0
	ds_read_b128 v[122:125], v117 offset:6912
	ds_read_b128 v[138:141], v117 offset:6976
	s_setprio 1
	s_waitcnt lgkmcnt(3)
	v_mfma_f32_16x16x32_bf16 v[72:75], v[130:133], v[76:79], v[126:129]
	s_waitcnt lgkmcnt(2)
	v_mfma_f32_16x16x32_bf16 v[72:75], v[134:137], v[80:83], v[72:75]
	s_setprio 0
	s_setprio 1
	s_waitcnt lgkmcnt(1)
	v_mfma_f32_16x16x32_bf16 v[76:79], v[122:125], v[76:79], v[126:129]
	s_waitcnt lgkmcnt(0)
	v_mfma_f32_16x16x32_bf16 v[76:79], v[138:141], v[80:83], v[76:79]
	s_setprio 0
	s_and_b64 vcc, exec, s[72:73]
	s_cbranch_vccnz .LBB0_1067
	v_add_u32_e32 v80, v120, v111
	v_cmp_lt_i32_e32 vcc, -1, v80
	s_nop 1
	v_cndmask_b32_e32 v64, v222, v64, vcc
	v_cmp_lt_i32_e32 vcc, 0, v80
	s_nop 1
	v_cndmask_b32_e32 v65, v222, v65, vcc
	v_cmp_lt_i32_e32 vcc, 1, v80
	s_nop 1
	v_cndmask_b32_e32 v66, v222, v66, vcc
	v_cmp_lt_i32_e32 vcc, 2, v80
	s_nop 1
	v_cndmask_b32_e32 v67, v222, v67, vcc
	v_cmp_lt_i32_e32 vcc, 15, v80
	s_nop 1
	v_cndmask_b32_e32 v68, v222, v68, vcc
	v_cmp_lt_i32_e32 vcc, 16, v80
	s_nop 1
	v_cndmask_b32_e32 v69, v222, v69, vcc
	v_cmp_lt_i32_e32 vcc, 17, v80
	s_nop 1
	v_cndmask_b32_e32 v70, v222, v70, vcc
	v_cmp_lt_i32_e32 vcc, 18, v80
	s_nop 1
	v_cndmask_b32_e32 v71, v222, v71, vcc
	v_cmp_lt_i32_e32 vcc, 31, v80
	s_nop 1
	v_cndmask_b32_e32 v72, v222, v72, vcc
	v_cmp_lt_i32_e32 vcc, 32, v80
	s_nop 1
	v_cndmask_b32_e32 v73, v222, v73, vcc
	v_cmp_lt_i32_e32 vcc, 33, v80
	s_nop 1
	v_cndmask_b32_e32 v74, v222, v74, vcc
	v_cmp_lt_i32_e32 vcc, 34, v80
	s_nop 1
	v_cndmask_b32_e32 v75, v222, v75, vcc
	v_cmp_lt_i32_e32 vcc, 47, v80
	s_nop 1
	v_cndmask_b32_e32 v76, v222, v76, vcc
	v_cmp_lt_i32_e32 vcc, 48, v80
	s_nop 1
	v_cndmask_b32_e32 v77, v222, v77, vcc
	v_cmp_lt_i32_e32 vcc, 49, v80
	s_nop 1
	v_cndmask_b32_e32 v78, v222, v78, vcc
	v_cmp_lt_i32_e32 vcc, 50, v80
	s_nop 1
	v_cndmask_b32_e32 v79, v222, v79, vcc

; #define LAS __attribute__((address_space(3)))
; #define MFMA16(a, b, c) __builtin_amdgcn_mfma_f32_16x16x32_bf16((a), (b), (c), 0, 0, 0)
; __device__ __forceinline__ void sel_group(const LAS bf16_t* Kt, const LAS bf16_t* Vt, LAS float* S, const bf16x8 qB0, const bf16x8 qB1, int jc, int rc, bool valid, bool masked, int tw64, int lr, int q) {
;     LAS float* Srow = S + (jc * 3 + rc) * 68;
;     const float mref = Srow[65]; const bool st = Srow[66] != 0.f;
;     f32x4 acc[4];
; #pragma unroll
;     for (int dt = 0; dt < 4; ++dt) acc[dt] = *(const LAS f32x4*)(Srow + 16 * dt + 4 * q);
;     float lc = Srow[64];
;     const float nm = valid ? -mref : -1e30f;
;     const f32x4 c0 = (f32x4){nm, nm, nm, nm};
;     const LAS bf16_t* kbase = Kt + lr * 72 + 8 * q;
;     f32x4 s[4];
;     {
;         bf16x8 kf[2][2];
;         kf[0][0] = *(const LAS bf16x8*)(kbase); kf[0][1] = *(const LAS bf16x8*)(kbase + 32);
; #pragma unroll
;         for (int mt = 0; mt < 4; ++mt) {
;             if (mt < 3) { kf[(mt + 1) & 1][0] = *(const LAS bf16x8*)(kbase + 16 * (mt + 1) * 72); kf[(mt + 1) & 1][1] = *(const LAS bf16x8*)(kbase + 16 * (mt + 1) * 72 + 32); }
;             __builtin_amdgcn_sched_barrier(0);
;             __builtin_amdgcn_s_setprio(1); s[mt] = MFMA16(kf[mt & 1][0], qB0, c0); s[mt] = MFMA16(kf[mt & 1][1], qB1, s[mt]); __builtin_amdgcn_s_setprio(0);
;             __builtin_amdgcn_sched_barrier(0);
;         }
;     }
;     if (masked) {
;         const int hq = tw64 + jc - 4 * q;
; #pragma unroll
;         for (int mt = 0; mt < 4; ++mt)
; #pragma unroll
;             for (int i = 0; i < 4; ++i) s[mt][i] = ((16 * mt + i) <= hq) ? s[mt][i] : -1e30f;
.LBB0_1078:
	s_cmp_lt_u32 s10, 6
	s_cbranch_scc1 .LBB0_1092
	v_mad_u64_u32 v[48:49], s[4:5], v118, 3, v[92:93]
	v_mul_lo_u32 v48, v48, s36
	v_add_u32_e32 v79, s49, v48
	v_add_u32_e32 v48, v79, v97
	ds_read_b96 v[76:78], v79 offset:46336
	ds_read_b128 v[60:63], v48 offset:46080
	ds_read_b128 v[56:59], v48 offset:46144
	ds_read_b128 v[52:55], v48 offset:46208
	ds_read_b128 v[48:51], v48 offset:46272
	ds_read_b128 v[64:67], v117
	ds_read_b128 v[68:71], v117 offset:64
	ds_read_b128 v[72:75], v117 offset:2304
	ds_read_b128 v[80:83], v117 offset:2368
	s_waitcnt lgkmcnt(8)
	v_cndmask_b32_e64 v120, v222, -v77, s[74:75]
	v_mov_b32_e32 v121, v120
	v_mov_b32_e32 v122, v120
	v_mov_b32_e32 v123, v120
	s_setprio 1
	s_waitcnt lgkmcnt(3)
	v_mfma_f32_16x16x32_bf16 v[64:67], v[64:67], v[40:43], v[120:123]
	s_waitcnt lgkmcnt(2)
	v_mfma_f32_16x16x32_bf16 v[64:67], v[68:71], v[44:47], v[64:67]
	s_setprio 0
	ds_read_b128 v[124:127], v117 offset:4608
	ds_read_b128 v[128:131], v117 offset:4672
	s_setprio 1
	s_waitcnt lgkmcnt(3)
	v_mfma_f32_16x16x32_bf16 v[68:71], v[72:75], v[40:43], v[120:123]
	s_waitcnt lgkmcnt(2)
	v_mfma_f32_16x16x32_bf16 v[68:71], v[80:83], v[44:47], v[68:71]
	s_setprio 0
	ds_read_b128 v[80:83], v117 offset:6912
	ds_read_b128 v[132:135], v117 offset:6976
	s_setprio 1
	s_waitcnt lgkmcnt(3)
	v_mfma_f32_16x16x32_bf16 v[72:75], v[124:127], v[40:43], v[120:123]
	s_waitcnt lgkmcnt(2)
	v_mfma_f32_16x16x32_bf16 v[72:75], v[128:131], v[44:47], v[72:75]
	s_setprio 0
	s_setprio 1
	s_waitcnt lgkmcnt(1)
	v_mfma_f32_16x16x32_bf16 v[40:43], v[80:83], v[40:43], v[120:123]
	s_waitcnt lgkmcnt(0)
	v_mfma_f32_16x16x32_bf16 v[40:43], v[132:135], v[44:47], v[40:43]
	s_setprio 0
	s_and_b64 vcc, exec, s[72:73]
	s_cbranch_vccnz .LBB0_1081
	v_add_u32_e32 v44, v118, v111
	v_cmp_lt_i32_e32 vcc, -1, v44
	s_nop 1
	v_cndmask_b32_e32 v64, v222, v64, vcc
	v_cmp_lt_i32_e32 vcc, 0, v44
	s_nop 1
	v_cndmask_b32_e32 v65, v222, v65, vcc
	v_cmp_lt_i32_e32 vcc, 1, v44
	s_nop 1
	v_cndmask_b32_e32 v66, v222, v66, vcc
	v_cmp_lt_i32_e32 vcc, 2, v44
	s_nop 1
	v_cndmask_b32_e32 v67, v222, v67, vcc
	v_cmp_lt_i32_e32 vcc, 15, v44
	s_nop 1
	v_cndmask_b32_e32 v68, v222, v68, vcc
	v_cmp_lt_i32_e32 vcc, 16, v44
	s_nop 1
	v_cndmask_b32_e32 v69, v222, v69, vcc
	v_cmp_lt_i32_e32 vcc, 17, v44
	s_nop 1
	v_cndmask_b32_e32 v70, v222, v70, vcc
	v_cmp_lt_i32_e32 vcc, 18, v44
	s_nop 1
	v_cndmask_b32_e32 v71, v222, v71, vcc
	v_cmp_lt_i32_e32 vcc, 31, v44
	s_nop 1
	v_cndmask_b32_e32 v72, v222, v72, vcc
	v_cmp_lt_i32_e32 vcc, 32, v44
	s_nop 1
	v_cndmask_b32_e32 v73, v222, v73, vcc
	v_cmp_lt_i32_e32 vcc, 33, v44
	s_nop 1
	v_cndmask_b32_e32 v74, v222, v74, vcc
	v_cmp_lt_i32_e32 vcc, 34, v44
	s_nop 1
	v_cndmask_b32_e32 v75, v222, v75, vcc
	v_cmp_lt_i32_e32 vcc, 47, v44
	s_nop 1
	v_cndmask_b32_e32 v40, v222, v40, vcc
	v_cmp_lt_i32_e32 vcc, 48, v44
	s_nop 1
	v_cndmask_b32_e32 v41, v222, v41, vcc
	v_cmp_lt_i32_e32 vcc, 49, v44
	s_nop 1
	v_cndmask_b32_e32 v42, v222, v42, vcc
	v_cmp_lt_i32_e32 vcc, 50, v44
	s_nop 1
	v_cndmask_b32_e32 v43, v222, v43, vcc

; #define LAS __attribute__((address_space(3)))
; #define MFMA16(a, b, c) __builtin_amdgcn_mfma_f32_16x16x32_bf16((a), (b), (c), 0, 0, 0)
; __device__ __forceinline__ void sel_group(const LAS bf16_t* Kt, const LAS bf16_t* Vt, LAS float* S, const bf16x8 qB0, const bf16x8 qB1, int jc, int rc, bool valid, bool masked, int tw64, int lr, int q) {
;     LAS float* Srow = S + (jc * 3 + rc) * 68;
;     const float mref = Srow[65]; const bool st = Srow[66] != 0.f;
;     f32x4 acc[4];
; #pragma unroll
;     for (int dt = 0; dt < 4; ++dt) acc[dt] = *(const LAS f32x4*)(Srow + 16 * dt + 4 * q);
;     float lc = Srow[64];
;     const float nm = valid ? -mref : -1e30f;
;     const f32x4 c0 = (f32x4){nm, nm, nm, nm};
;     const LAS bf16_t* kbase = Kt + lr * 72 + 8 * q;
;     f32x4 s[4];
;     {
;         bf16x8 kf[2][2];
;         kf[0][0] = *(const LAS bf16x8*)(kbase); kf[0][1] = *(const LAS bf16x8*)(kbase + 32);
; #pragma unroll
;         for (int mt = 0; mt < 4; ++mt) {
;             if (mt < 3) { kf[(mt + 1) & 1][0] = *(const LAS bf16x8*)(kbase + 16 * (mt + 1) * 72); kf[(mt + 1) & 1][1] = *(const LAS bf16x8*)(kbase + 16 * (mt + 1) * 72 + 32); }
;             __builtin_amdgcn_sched_barrier(0);
;             __builtin_amdgcn_s_setprio(1); s[mt] = MFMA16(kf[mt & 1][0], qB0, c0); s[mt] = MFMA16(kf[mt & 1][1], qB1, s[mt]); __builtin_amdgcn_s_setprio(0);
;             __builtin_amdgcn_sched_barrier(0);
;         }
;     }
;     if (masked) {
;         const int hq = tw64 + jc - 4 * q;
; #pragma unroll
;         for (int mt = 0; mt < 4; ++mt)
; #pragma unroll
;             for (int i = 0; i < 4; ++i) s[mt][i] = ((16 * mt + i) <= hq) ? s[mt][i] : -1e30f;
.LBB0_1092:
	s_cmp_lt_u32 s10, 11
	s_cbranch_scc1 .LBB0_1057
	s_nop 0
	v_mad_u64_u32 v[40:41], s[4:5], v116, 3, v[96:97]
	v_mul_lo_u32 v40, v40, s36
	v_add_u32_e32 v71, s49, v40
	v_add_u32_e32 v40, v71, v97
	ds_read_b96 v[68:70], v71 offset:46336
	ds_read_b128 v[52:55], v40 offset:46080
	ds_read_b128 v[48:51], v40 offset:46144
	ds_read_b128 v[44:47], v40 offset:46208
	ds_read_b128 v[40:43], v40 offset:46272
	ds_read_b128 v[56:59], v117
	ds_read_b128 v[60:63], v117 offset:64
	ds_read_b128 v[64:67], v117 offset:2304
	ds_read_b128 v[72:75], v117 offset:2368
	s_waitcnt lgkmcnt(8)
	v_cndmask_b32_e64 v76, v222, -v69, s[70:71]
	v_mov_b32_e32 v77, v76
	v_mov_b32_e32 v78, v76
	v_mov_b32_e32 v79, v76
	s_setprio 1
	s_waitcnt lgkmcnt(3)
	v_mfma_f32_16x16x32_bf16 v[56:59], v[56:59], v[32:35], v[76:79]
	s_waitcnt lgkmcnt(2)
	v_mfma_f32_16x16x32_bf16 v[56:59], v[60:63], v[36:39], v[56:59]
	s_setprio 0
	ds_read_b128 v[80:83], v117 offset:4608
	ds_read_b128 v[118:121], v117 offset:4672
	s_setprio 1
	s_waitcnt lgkmcnt(3)
	v_mfma_f32_16x16x32_bf16 v[60:63], v[64:67], v[32:35], v[76:79]
	s_waitcnt lgkmcnt(2)
	v_mfma_f32_16x16x32_bf16 v[60:63], v[72:75], v[36:39], v[60:63]
	s_setprio 0
	ds_read_b128 v[72:75], v117 offset:6912
	ds_read_b128 v[122:125], v117 offset:6976
	s_setprio 1
	s_waitcnt lgkmcnt(3)
	v_mfma_f32_16x16x32_bf16 v[64:67], v[80:83], v[32:35], v[76:79]
	s_waitcnt lgkmcnt(2)
	v_mfma_f32_16x16x32_bf16 v[64:67], v[118:121], v[36:39], v[64:67]
	s_setprio 0
	s_setprio 1
	s_waitcnt lgkmcnt(1)
	v_mfma_f32_16x16x32_bf16 v[32:35], v[72:75], v[32:35], v[76:79]
	s_waitcnt lgkmcnt(0)
	v_mfma_f32_16x16x32_bf16 v[32:35], v[122:125], v[36:39], v[32:35]
	s_setprio 0
	s_and_b64 vcc, exec, s[72:73]
	s_cbranch_vccnz .LBB0_1095
	v_add_u32_e32 v36, v116, v111
	v_cmp_lt_i32_e32 vcc, -1, v36
	s_nop 1
	v_cndmask_b32_e32 v56, v222, v56, vcc
	v_cmp_lt_i32_e32 vcc, 0, v36
	s_nop 1
	v_cndmask_b32_e32 v57, v222, v57, vcc
	v_cmp_lt_i32_e32 vcc, 1, v36
	s_nop 1
	v_cndmask_b32_e32 v58, v222, v58, vcc
	v_cmp_lt_i32_e32 vcc, 2, v36
	s_nop 1
	v_cndmask_b32_e32 v59, v222, v59, vcc
	v_cmp_lt_i32_e32 vcc, 15, v36
	s_nop 1
	v_cndmask_b32_e32 v60, v222, v60, vcc
	v_cmp_lt_i32_e32 vcc, 16, v36
	s_nop 1
	v_cndmask_b32_e32 v61, v222, v61, vcc
	v_cmp_lt_i32_e32 vcc, 17, v36
	s_nop 1
	v_cndmask_b32_e32 v62, v222, v62, vcc
	v_cmp_lt_i32_e32 vcc, 18, v36
	s_nop 1
	v_cndmask_b32_e32 v63, v222, v63, vcc
	v_cmp_lt_i32_e32 vcc, 31, v36
	s_nop 1
	v_cndmask_b32_e32 v64, v222, v64, vcc
	v_cmp_lt_i32_e32 vcc, 32, v36
	s_nop 1
	v_cndmask_b32_e32 v65, v222, v65, vcc
	v_cmp_lt_i32_e32 vcc, 33, v36
	s_nop 1
	v_cndmask_b32_e32 v66, v222, v66, vcc
	v_cmp_lt_i32_e32 vcc, 34, v36
	s_nop 1
	v_cndmask_b32_e32 v67, v222, v67, vcc
	v_cmp_lt_i32_e32 vcc, 47, v36
	s_nop 1
	v_cndmask_b32_e32 v32, v222, v32, vcc
	v_cmp_lt_i32_e32 vcc, 48, v36
	s_nop 1
	v_cndmask_b32_e32 v33, v222, v33, vcc
	v_cmp_lt_i32_e32 vcc, 49, v36
	s_nop 1
	v_cndmask_b32_e32 v34, v222, v34, vcc
	v_cmp_lt_i32_e32 vcc, 50, v36
	s_nop 1
	v_cndmask_b32_e32 v35, v222, v35, vcc

; #define GAS __attribute__((address_space(1)))
; __device__ __forceinline__ float row_rinv16(const float* ssq, int row) {
;     const GAS f32x4* p = (const GAS f32x4*)(ssq + (size_t)row * 16); const f32x4 a = p[0], b = p[1], c = p[2], d = p[3];
;     const float s = (((a[0] + a[1]) + (a[2] + a[3])) + ((b[0] + b[1]) + (b[2] + b[3]))) + (((c[0] + c[1]) + (c[2] + c[3])) + ((d[0] + d[1]) + (d[2] + d[3])));
;     return __builtin_amdgcn_rsqf(s * (1.0f / 1024.0f) + NORM_EPS);
;     __device__ __forceinline__ void operator()(const f32x4 (&acc)[2][2][4][2], const Unit& u, int wr, int wc, int fr, int fq) const {
; #pragma unroll
;         for (int ai = 0; ai < 2; ++ai)
; #pragma unroll
;             for (int m = 0; m < 4; ++m) {
;                 const int row = u.pm * BM + ai * HALF + wr * 64 + m * 16 + fr;
;                 const float rinv = row_rinv16(ssq, row);
;                 const float a = rinv * -1.4426950408889634f, r2 = rinv * rinv;
;                 u32x4 w;
;                 w.x = swiglu2(acc[ai][0][m][0][0], acc[ai][0][m][0][1], acc[ai][1][m][0][0], acc[ai][1][m][0][1], a, r2);
;                 w.y = swiglu2(acc[ai][0][m][0][2], acc[ai][0][m][0][3], acc[ai][1][m][0][2], acc[ai][1][m][0][3], a, r2);
;                 w.z = swiglu2(acc[ai][0][m][1][0], acc[ai][0][m][1][1], acc[ai][1][m][1][0], acc[ai][1][m][1][1], a, r2);
;                 w.w = swiglu2(acc[ai][0][m][1][2], acc[ai][0][m][1][3], acc[ai][1][m][1][2], acc[ai][1][m][1][3], a, r2);
;                 *(GAS u32x4*)(hid + (size_t)row * 2816 + u.pn * 128 + wc * 32 + 8 * fq) = w;
.LBB0_1388:
	v_lshl_add_u32 v140, s31, 8, v143
	v_mbcnt_lo_u32_b32 v168, -1, 0
	v_mbcnt_hi_u32_b32 v168, -1, v168
	v_and_b32_e32 v168, 48, v168
	v_lshl_add_u32 v168, v140, 6, v168
	v_add_u32_e32 v169, 0x2000, v168
	global_load_dwordx4 v[172:175], v168, s[6:7]
	global_load_dwordx4 v[176:179], v168, s[6:7] offset:1024
	global_load_dwordx4 v[180:183], v168, s[6:7] offset:2048
	global_load_dwordx4 v[184:187], v168, s[6:7] offset:3072
	global_load_dwordx4 v[200:203], v169, s[6:7]
	global_load_dwordx4 v[204:207], v169, s[6:7] offset:1024
	global_load_dwordx4 v[208:211], v169, s[6:7] offset:2048
	global_load_dwordx4 v[212:215], v169, s[6:7] offset:3072
	v_pk_mul_f32 v[120:121], v[124:125], v[120:121]
	v_pk_mul_f32 v[122:123], v[126:127], v[122:123]
	v_pk_mul_f32 v[112:113], v[116:117], v[112:113]
	v_pk_mul_f32 v[114:115], v[118:119], v[114:115]
	s_lshl_b32 s2, s30, 7
	s_ashr_i32 s3, s2, 31
	s_movk_i32 s14, 0x1600
	s_lshl_b64 s[30:31], s[2:3], 1
	v_pk_mul_f32 v[104:105], v[108:109], v[104:105]
	v_pk_mul_f32 v[106:107], v[110:111], v[106:107]
	v_pk_mul_f32 v[96:97], v[100:101], v[96:97]
	v_pk_mul_f32 v[98:99], v[102:103], v[98:99]
	v_pk_mul_f32 v[88:89], v[92:93], v[88:89]
	v_pk_mul_f32 v[90:91], v[94:95], v[90:91]
	v_pk_mul_f32 v[80:81], v[84:85], v[80:81]
	v_pk_mul_f32 v[82:83], v[86:87], v[82:83]
	v_pk_mul_f32 v[72:73], v[76:77], v[72:73]
	v_pk_mul_f32 v[74:75], v[78:79], v[74:75]
	v_pk_mul_f32 v[64:65], v[68:69], v[64:65]
	v_pk_mul_f32 v[66:67], v[70:71], v[66:67]
	v_pk_mul_f32 v[56:57], v[60:61], v[56:57]
	v_pk_mul_f32 v[58:59], v[62:63], v[58:59]
	v_pk_mul_f32 v[48:49], v[52:53], v[48:49]
	v_pk_mul_f32 v[50:51], v[54:55], v[50:51]
	v_pk_mul_f32 v[40:41], v[44:45], v[40:41]
	v_pk_mul_f32 v[42:43], v[46:47], v[42:43]
	v_pk_mul_f32 v[32:33], v[36:37], v[32:33]
	v_pk_mul_f32 v[34:35], v[38:39], v[34:35]
	v_pk_mul_f32 v[24:25], v[28:29], v[24:25]
	v_pk_mul_f32 v[26:27], v[30:31], v[26:27]
	v_pk_mul_f32 v[16:17], v[20:21], v[16:17]
	v_pk_mul_f32 v[18:19], v[22:23], v[18:19]
	v_pk_mul_f32 v[8:9], v[12:13], v[8:9]
	v_pk_mul_f32 v[10:11], v[14:15], v[10:11]
	v_pk_mul_f32 v[0:1], v[4:5], v[0:1]
	v_pk_mul_f32 v[2:3], v[6:7], v[2:3]
	v_readlane_b32 s56, v255, 17
	s_andn2_b64 vcc, exec, s[42:43]
	v_readlane_b32 s57, v255, 18
	v_readlane_b32 s58, v255, 19
	v_readlane_b32 s59, v255, 20
	s_waitcnt vmcnt(0)
	v_pk_add_f32 v[172:173], v[172:173], v[174:175]
	v_pk_add_f32 v[176:177], v[176:177], v[178:179]
	v_pk_add_f32 v[180:181], v[180:181], v[182:183]
	v_pk_add_f32 v[184:185], v[184:185], v[186:187]
	v_pk_add_f32 v[200:201], v[200:201], v[202:203]
	v_pk_add_f32 v[204:205], v[204:205], v[206:207]
	v_pk_add_f32 v[208:209], v[208:209], v[210:211]
	v_pk_add_f32 v[212:213], v[212:213], v[214:215]
	v_add_f32_e32 v172, v172, v173
	v_add_f32_e32 v176, v176, v177
	v_add_f32_e32 v180, v180, v181
	v_add_f32_e32 v184, v184, v185
	v_add_f32_e32 v200, v200, v201
	v_add_f32_e32 v204, v204, v205
	v_add_f32_e32 v208, v208, v209
	v_add_f32_e32 v212, v212, v213
	v_mov_b32_e32 v173, v172
	v_mov_b32_e32 v177, v176
	v_mov_b32_e32 v181, v180
	v_mov_b32_e32 v185, v184
	v_mov_b32_e32 v201, v200
	v_mov_b32_e32 v205, v204
	v_mov_b32_e32 v209, v208
	v_mov_b32_e32 v213, v212
	v_permlane16_swap_b32_e32 v172, v173
	v_permlane16_swap_b32_e32 v176, v177
	v_permlane16_swap_b32_e32 v180, v181
	v_permlane16_swap_b32_e32 v184, v185
	v_permlane16_swap_b32_e32 v200, v201
	v_permlane16_swap_b32_e32 v204, v205
	v_permlane16_swap_b32_e32 v208, v209
	v_permlane16_swap_b32_e32 v212, v213
	v_add_f32_e32 v172, v172, v173
	v_add_f32_e32 v176, v176, v177
	v_add_f32_e32 v180, v180, v181
	v_add_f32_e32 v184, v184, v185
	v_add_f32_e32 v200, v200, v201
	v_add_f32_e32 v204, v204, v205
	v_add_f32_e32 v208, v208, v209
	v_add_f32_e32 v212, v212, v213
	v_mov_b32_e32 v173, v172
	v_mov_b32_e32 v177, v176
	v_mov_b32_e32 v181, v180
	v_mov_b32_e32 v185, v184
	v_mov_b32_e32 v201, v200
	v_mov_b32_e32 v205, v204
	v_mov_b32_e32 v209, v208
	v_mov_b32_e32 v213, v212
	v_permlane32_swap_b32_e32 v172, v173
	v_permlane32_swap_b32_e32 v176, v177
	v_permlane32_swap_b32_e32 v180, v181
	v_permlane32_swap_b32_e32 v184, v185
	v_permlane32_swap_b32_e32 v200, v201
	v_permlane32_swap_b32_e32 v204, v205
	v_permlane32_swap_b32_e32 v208, v209
	v_permlane32_swap_b32_e32 v212, v213
	v_add_f32_e32 v172, v172, v173
	v_add_f32_e32 v176, v176, v177
	v_add_f32_e32 v180, v180, v181
	v_add_f32_e32 v184, v184, v185
	v_add_f32_e32 v200, v200, v201
	v_add_f32_e32 v204, v204, v205
	v_add_f32_e32 v208, v208, v209
	v_add_f32_e32 v212, v212, v213
	v_fmamk_f32 v172, v172, 0x3a800000, v220
	v_fmamk_f32 v176, v176, 0x3a800000, v220
	v_fmamk_f32 v180, v180, 0x3a800000, v220
	v_fmamk_f32 v184, v184, 0x3a800000, v220
	v_fmamk_f32 v200, v200, 0x3a800000, v220
	v_fmamk_f32 v204, v204, 0x3a800000, v220
	v_fmamk_f32 v208, v208, 0x3a800000, v220
	v_fmamk_f32 v212, v212, 0x3a800000, v220
	v_rsq_f32_e32 v172, v172
	v_rsq_f32_e32 v176, v176
	v_rsq_f32_e32 v180, v180
	v_rsq_f32_e32 v184, v184
	v_rsq_f32_e32 v200, v200
	v_rsq_f32_e32 v204, v204
	v_rsq_f32_e32 v208, v208
	v_rsq_f32_e32 v212, v212
	v_mov_b32_e32 v141, v172
	v_mul_f32_e32 v144, 0xbfb8aa3b, v141
	v_pk_mul_f32 v[148:149], v[124:125], v[144:145] op_sel_hi:[1,0]
	v_mul_f32_e32 v142, v141, v141
	v_exp_f32_e32 v148, v148
	v_exp_f32_e32 v149, v149
	s_nop 0
	v_pk_add_f32 v[148:149], v[148:149], 1.0 op_sel_hi:[1,0]
	s_nop 0
	v_rcp_f32_e32 v148, v148
	v_rcp_f32_e32 v149, v149
	s_nop 0
	v_pk_mul_f32 v[124:125], v[142:143], v[148:149] op_sel_hi:[0,1]
	v_pk_mul_f32 v[120:121], v[120:121], v[124:125]
	v_pk_mul_f32 v[124:125], v[126:127], v[144:145] op_sel_hi:[1,0]
	v_cvt_pk_bf16_f32 v120, v120, v121
	s_nop 0
; #define GAS __attribute__((address_space(1)))
;     __device__ __forceinline__ void operator()(const f32x4 (&acc)[2][2][4][2], const Unit& u, int wr, int wc, int fr, int fq) const {
;     ...
;             for (int m = 0; m < 4; ++m) {
;                 const int row = u.pm * BM + ai * HALF + wr * 64 + m * 16 + fr;
;                 const float rinv = row_rinv16(ssq, row);
;                 const float a = rinv * -1.4426950408889634f, r2 = rinv * rinv;
;                 u32x4 w;
;                 w.x = swiglu2(acc[ai][0][m][0][0], acc[ai][0][m][0][1], acc[ai][1][m][0][0], acc[ai][1][m][0][1], a, r2);
;                 w.y = swiglu2(acc[ai][0][m][0][2], acc[ai][0][m][0][3], acc[ai][1][m][0][2], acc[ai][1][m][0][3], a, r2);
;                 w.z = swiglu2(acc[ai][0][m][1][0], acc[ai][0][m][1][1], acc[ai][1][m][1][0], acc[ai][1][m][1][1], a, r2);
;                 w.w = swiglu2(acc[ai][0][m][1][2], acc[ai][0][m][1][3], acc[ai][1][m][1][2], acc[ai][1][m][1][3], a, r2);
;                 *(GAS u32x4*)(hid + (size_t)row * 2816 + u.pn * 128 + wc * 32 + 8 * fq) = w;
	v_exp_f32_e32 v124, v124
	v_exp_f32_e32 v125, v125
	s_nop 0
	v_pk_add_f32 v[124:125], v[124:125], 1.0 op_sel_hi:[1,0]
	s_nop 0
	v_rcp_f32_e32 v124, v124
	v_rcp_f32_e32 v125, v125
	s_nop 0
	v_pk_mul_f32 v[124:125], v[142:143], v[124:125] op_sel_hi:[0,1]
	v_pk_mul_f32 v[122:123], v[122:123], v[124:125]
	s_nop 0
	v_cvt_pk_bf16_f32 v121, v122, v123
	v_pk_mul_f32 v[122:123], v[116:117], v[144:145] op_sel_hi:[1,0]
	s_nop 0
	v_exp_f32_e32 v122, v122
	v_exp_f32_e32 v123, v123
	s_nop 0
	v_pk_add_f32 v[122:123], v[122:123], 1.0 op_sel_hi:[1,0]
	s_nop 0
	v_rcp_f32_e32 v122, v122
	v_rcp_f32_e32 v123, v123
	s_nop 0
	v_pk_mul_f32 v[116:117], v[142:143], v[122:123] op_sel_hi:[0,1]
	v_pk_mul_f32 v[112:113], v[112:113], v[116:117]
	s_nop 0
	v_cvt_pk_bf16_f32 v122, v112, v113
	v_pk_mul_f32 v[112:113], v[118:119], v[144:145] op_sel_hi:[1,0]
	s_nop 0
	v_exp_f32_e32 v112, v112
	v_exp_f32_e32 v113, v113
	s_nop 0
	v_pk_add_f32 v[112:113], v[112:113], 1.0 op_sel_hi:[1,0]
	s_nop 0
	v_rcp_f32_e32 v112, v112
	v_rcp_f32_e32 v113, v113
	s_nop 0
	v_pk_mul_f32 v[112:113], v[142:143], v[112:113] op_sel_hi:[0,1]
	v_pk_mul_f32 v[112:113], v[114:115], v[112:113]
	s_nop 0
	v_cvt_pk_bf16_f32 v123, v112, v113
	v_mov_b64_e32 v[112:113], s[8:9]
	v_mad_i64_i32 v[114:115], s[12:13], v140, s14, v[112:113]
	v_lshl_add_u64 v[114:115], v[114:115], 0, s[30:31]
	v_lshl_add_u64 v[114:115], v[114:115], 0, s[38:39]
	v_lshl_add_u64 v[114:115], v[114:115], 0, v[190:191]
	global_store_dwordx4 v[114:115], v[120:123], off
	v_or_b32_e32 v114, 16, v140
	v_mov_b32_e32 v115, v176
	v_mul_f32_e32 v118, 0xbfb8aa3b, v115
	v_pk_mul_f32 v[120:121], v[108:109], v[118:119] op_sel_hi:[1,0]
	v_mul_f32_e32 v116, v115, v115
	v_exp_f32_e32 v120, v120
	v_exp_f32_e32 v121, v121
	s_nop 0
	v_pk_add_f32 v[120:121], v[120:121], 1.0 op_sel_hi:[1,0]
	s_nop 0
	v_rcp_f32_e32 v120, v120
	v_rcp_f32_e32 v121, v121
	s_nop 0
	v_pk_mul_f32 v[108:109], v[116:117], v[120:121] op_sel_hi:[0,1]
	v_pk_mul_f32 v[104:105], v[104:105], v[108:109]
	v_pk_mul_f32 v[108:109], v[110:111], v[118:119] op_sel_hi:[1,0]
	v_cvt_pk_bf16_f32 v104, v104, v105
	s_nop 0
	v_exp_f32_e32 v108, v108
	v_exp_f32_e32 v109, v109
	s_nop 0
	v_pk_add_f32 v[108:109], v[108:109], 1.0 op_sel_hi:[1,0]
	s_nop 0
	v_rcp_f32_e32 v108, v108
	v_rcp_f32_e32 v109, v109
	s_nop 0
	v_pk_mul_f32 v[108:109], v[116:117], v[108:109] op_sel_hi:[0,1]
	v_pk_mul_f32 v[106:107], v[106:107], v[108:109]
	s_nop 0
	v_cvt_pk_bf16_f32 v105, v106, v107
	v_pk_mul_f32 v[106:107], v[100:101], v[118:119] op_sel_hi:[1,0]
	s_nop 0
	v_exp_f32_e32 v106, v106
	v_exp_f32_e32 v107, v107
	s_nop 0
	v_pk_add_f32 v[106:107], v[106:107], 1.0 op_sel_hi:[1,0]
	s_nop 0
	v_rcp_f32_e32 v106, v106
	v_rcp_f32_e32 v107, v107
	s_nop 0
	v_pk_mul_f32 v[100:101], v[116:117], v[106:107] op_sel_hi:[0,1]
	v_pk_mul_f32 v[96:97], v[96:97], v[100:101]
	s_nop 0
	v_cvt_pk_bf16_f32 v106, v96, v97
	v_pk_mul_f32 v[96:97], v[102:103], v[118:119] op_sel_hi:[1,0]
	s_nop 0
	v_exp_f32_e32 v96, v96
	v_exp_f32_e32 v97, v97
	s_nop 0
	v_pk_add_f32 v[96:97], v[96:97], 1.0 op_sel_hi:[1,0]
	s_nop 0
	v_rcp_f32_e32 v96, v96
	v_rcp_f32_e32 v97, v97
	s_nop 0
	v_pk_mul_f32 v[96:97], v[116:117], v[96:97] op_sel_hi:[0,1]
	v_pk_mul_f32 v[96:97], v[98:99], v[96:97]
	s_nop 0
	v_cvt_pk_bf16_f32 v107, v96, v97
	v_mad_i64_i32 v[96:97], s[2:3], v114, s14, v[112:113]
	v_lshl_add_u64 v[96:97], v[96:97], 0, s[30:31]
	v_lshl_add_u64 v[96:97], v[96:97], 0, s[38:39]
	v_lshl_add_u64 v[96:97], v[96:97], 0, v[190:191]
	global_store_dwordx4 v[96:97], v[104:107], off
	v_or_b32_e32 v96, 32, v140
	v_mov_b32_e32 v97, v180
	v_mul_f32_e32 v100, 0xbfb8aa3b, v97
	v_pk_mul_f32 v[102:103], v[92:93], v[100:101] op_sel_hi:[1,0]
	v_mul_f32_e32 v98, v97, v97
	v_exp_f32_e32 v102, v102
	v_exp_f32_e32 v103, v103
	s_nop 0
	v_pk_add_f32 v[102:103], v[102:103], 1.0 op_sel_hi:[1,0]
	s_nop 0
	v_rcp_f32_e32 v102, v102
	v_rcp_f32_e32 v103, v103
	s_nop 0
	v_pk_mul_f32 v[92:93], v[98:99], v[102:103] op_sel_hi:[0,1]
	v_pk_mul_f32 v[88:89], v[88:89], v[92:93]
	v_pk_mul_f32 v[92:93], v[94:95], v[100:101] op_sel_hi:[1,0]
	v_cvt_pk_bf16_f32 v88, v88, v89
	s_nop 0
	v_exp_f32_e32 v92, v92
	v_exp_f32_e32 v93, v93
	s_nop 0
	v_pk_add_f32 v[92:93], v[92:93], 1.0 op_sel_hi:[1,0]
	s_nop 0
	v_rcp_f32_e32 v92, v92
	v_rcp_f32_e32 v93, v93
	s_nop 0
	v_pk_mul_f32 v[92:93], v[98:99], v[92:93] op_sel_hi:[0,1]
	v_pk_mul_f32 v[90:91], v[90:91], v[92:93]
	s_nop 0
	v_cvt_pk_bf16_f32 v89, v90, v91
	v_pk_mul_f32 v[90:91], v[84:85], v[100:101] op_sel_hi:[1,0]
	s_nop 0
	v_exp_f32_e32 v90, v90
	v_exp_f32_e32 v91, v91
	s_nop 0
	v_pk_add_f32 v[90:91], v[90:91], 1.0 op_sel_hi:[1,0]
	s_nop 0
	v_rcp_f32_e32 v90, v90
	v_rcp_f32_e32 v91, v91
	s_nop 0
	v_pk_mul_f32 v[84:85], v[98:99], v[90:91] op_sel_hi:[0,1]
	v_pk_mul_f32 v[80:81], v[80:81], v[84:85]
	s_nop 0
	v_cvt_pk_bf16_f32 v90, v80, v81
	v_pk_mul_f32 v[80:81], v[86:87], v[100:101] op_sel_hi:[1,0]
	s_nop 0
	v_exp_f32_e32 v80, v80
	v_exp_f32_e32 v81, v81
	s_nop 0
	v_pk_add_f32 v[80:81], v[80:81], 1.0 op_sel_hi:[1,0]
	s_nop 0
	v_rcp_f32_e32 v80, v80
	v_rcp_f32_e32 v81, v81
	s_nop 0
	v_pk_mul_f32 v[80:81], v[98:99], v[80:81] op_sel_hi:[0,1]
	v_pk_mul_f32 v[80:81], v[82:83], v[80:81]
	s_nop 0
	v_cvt_pk_bf16_f32 v91, v80, v81
	v_mad_i64_i32 v[80:81], s[2:3], v96, s14, v[112:113]
	v_lshl_add_u64 v[80:81], v[80:81], 0, s[30:31]
	v_lshl_add_u64 v[80:81], v[80:81], 0, s[38:39]
	v_lshl_add_u64 v[80:81], v[80:81], 0, v[190:191]
	global_store_dwordx4 v[80:81], v[88:91], off
	v_or_b32_e32 v80, 48, v140
	v_mov_b32_e32 v81, v184
	v_mul_f32_e32 v84, 0xbfb8aa3b, v81
	v_pk_mul_f32 v[86:87], v[76:77], v[84:85] op_sel_hi:[1,0]
	v_mul_f32_e32 v82, v81, v81
	v_exp_f32_e32 v86, v86
; #define GAS __attribute__((address_space(1)))
;     __device__ __forceinline__ void operator()(const f32x4 (&acc)[2][2][4][2], const Unit& u, int wr, int wc, int fr, int fq) const {
;     ...
;             for (int m = 0; m < 4; ++m) {
;                 const int row = u.pm * BM + ai * HALF + wr * 64 + m * 16 + fr;
;                 const float rinv = row_rinv16(ssq, row);
;                 const float a = rinv * -1.4426950408889634f, r2 = rinv * rinv;
;                 u32x4 w;
;                 w.x = swiglu2(acc[ai][0][m][0][0], acc[ai][0][m][0][1], acc[ai][1][m][0][0], acc[ai][1][m][0][1], a, r2);
;                 w.y = swiglu2(acc[ai][0][m][0][2], acc[ai][0][m][0][3], acc[ai][1][m][0][2], acc[ai][1][m][0][3], a, r2);
;                 w.z = swiglu2(acc[ai][0][m][1][0], acc[ai][0][m][1][1], acc[ai][1][m][1][0], acc[ai][1][m][1][1], a, r2);
;                 w.w = swiglu2(acc[ai][0][m][1][2], acc[ai][0][m][1][3], acc[ai][1][m][1][2], acc[ai][1][m][1][3], a, r2);
;                 *(GAS u32x4*)(hid + (size_t)row * 2816 + u.pn * 128 + wc * 32 + 8 * fq) = w;
	v_exp_f32_e32 v87, v87
	s_nop 0
	v_pk_add_f32 v[86:87], v[86:87], 1.0 op_sel_hi:[1,0]
	s_nop 0
	v_rcp_f32_e32 v86, v86
	v_rcp_f32_e32 v87, v87
	s_nop 0
	v_pk_mul_f32 v[76:77], v[82:83], v[86:87] op_sel_hi:[0,1]
	v_pk_mul_f32 v[72:73], v[72:73], v[76:77]
	v_pk_mul_f32 v[76:77], v[78:79], v[84:85] op_sel_hi:[1,0]
	v_cvt_pk_bf16_f32 v72, v72, v73
	s_nop 0
	v_exp_f32_e32 v76, v76
	v_exp_f32_e32 v77, v77
	s_nop 0
	v_pk_add_f32 v[76:77], v[76:77], 1.0 op_sel_hi:[1,0]
	s_nop 0
	v_rcp_f32_e32 v76, v76
	v_rcp_f32_e32 v77, v77
	s_nop 0
	v_pk_mul_f32 v[76:77], v[82:83], v[76:77] op_sel_hi:[0,1]
	v_pk_mul_f32 v[74:75], v[74:75], v[76:77]
	s_nop 0
	v_cvt_pk_bf16_f32 v73, v74, v75
	v_pk_mul_f32 v[74:75], v[68:69], v[84:85] op_sel_hi:[1,0]
	s_nop 0
	v_exp_f32_e32 v74, v74
	v_exp_f32_e32 v75, v75
	s_nop 0
	v_pk_add_f32 v[74:75], v[74:75], 1.0 op_sel_hi:[1,0]
	s_nop 0
	v_rcp_f32_e32 v74, v74
	v_rcp_f32_e32 v75, v75
	s_nop 0
	v_pk_mul_f32 v[68:69], v[82:83], v[74:75] op_sel_hi:[0,1]
	v_pk_mul_f32 v[64:65], v[64:65], v[68:69]
	s_nop 0
	v_cvt_pk_bf16_f32 v74, v64, v65
	v_pk_mul_f32 v[64:65], v[70:71], v[84:85] op_sel_hi:[1,0]
	s_nop 0
	v_exp_f32_e32 v64, v64
	v_exp_f32_e32 v65, v65
	s_nop 0
	v_pk_add_f32 v[64:65], v[64:65], 1.0 op_sel_hi:[1,0]
	s_nop 0
	v_rcp_f32_e32 v64, v64
	v_rcp_f32_e32 v65, v65
	s_nop 0
	v_pk_mul_f32 v[64:65], v[82:83], v[64:65] op_sel_hi:[0,1]
	v_pk_mul_f32 v[64:65], v[66:67], v[64:65]
	s_nop 0
	v_cvt_pk_bf16_f32 v75, v64, v65
	v_mad_i64_i32 v[64:65], s[2:3], v80, s14, v[112:113]
	v_lshl_add_u64 v[64:65], v[64:65], 0, s[30:31]
	v_lshl_add_u64 v[64:65], v[64:65], 0, s[38:39]
	v_lshl_add_u64 v[64:65], v[64:65], 0, v[190:191]
	global_store_dwordx4 v[64:65], v[72:75], off
	v_add_u32_e32 v64, 0x80, v140
	v_mov_b32_e32 v65, v200
	v_mul_f32_e32 v68, 0xbfb8aa3b, v65
	v_pk_mul_f32 v[70:71], v[60:61], v[68:69] op_sel_hi:[1,0]
	v_mul_f32_e32 v66, v65, v65
	v_exp_f32_e32 v70, v70
	v_exp_f32_e32 v71, v71
	s_nop 0
	v_pk_add_f32 v[70:71], v[70:71], 1.0 op_sel_hi:[1,0]
	s_nop 0
	v_rcp_f32_e32 v70, v70
	v_rcp_f32_e32 v71, v71
	s_nop 0
	v_pk_mul_f32 v[60:61], v[66:67], v[70:71] op_sel_hi:[0,1]
	v_pk_mul_f32 v[56:57], v[56:57], v[60:61]
	v_pk_mul_f32 v[60:61], v[62:63], v[68:69] op_sel_hi:[1,0]
	v_cvt_pk_bf16_f32 v56, v56, v57
	s_nop 0
	v_exp_f32_e32 v60, v60
	v_exp_f32_e32 v61, v61
	s_nop 0
	v_pk_add_f32 v[60:61], v[60:61], 1.0 op_sel_hi:[1,0]
	s_nop 0
	v_rcp_f32_e32 v60, v60
	v_rcp_f32_e32 v61, v61
	s_nop 0
	v_pk_mul_f32 v[60:61], v[66:67], v[60:61] op_sel_hi:[0,1]
	v_pk_mul_f32 v[58:59], v[58:59], v[60:61]
	s_nop 0
	v_cvt_pk_bf16_f32 v57, v58, v59
	v_pk_mul_f32 v[58:59], v[52:53], v[68:69] op_sel_hi:[1,0]
	s_nop 0
	v_exp_f32_e32 v58, v58
	v_exp_f32_e32 v59, v59
	s_nop 0
	v_pk_add_f32 v[58:59], v[58:59], 1.0 op_sel_hi:[1,0]
	s_nop 0
	v_rcp_f32_e32 v58, v58
	v_rcp_f32_e32 v59, v59
	s_nop 0
	v_pk_mul_f32 v[52:53], v[66:67], v[58:59] op_sel_hi:[0,1]
	v_pk_mul_f32 v[48:49], v[48:49], v[52:53]
	s_nop 0
	v_cvt_pk_bf16_f32 v58, v48, v49
	v_pk_mul_f32 v[48:49], v[54:55], v[68:69] op_sel_hi:[1,0]
	s_nop 0
	v_exp_f32_e32 v48, v48
	v_exp_f32_e32 v49, v49
	s_nop 0
	v_pk_add_f32 v[48:49], v[48:49], 1.0 op_sel_hi:[1,0]
	s_nop 0
	v_rcp_f32_e32 v48, v48
	v_rcp_f32_e32 v49, v49
	s_nop 0
	v_pk_mul_f32 v[48:49], v[66:67], v[48:49] op_sel_hi:[0,1]
	v_pk_mul_f32 v[48:49], v[50:51], v[48:49]
	s_nop 0
	v_cvt_pk_bf16_f32 v59, v48, v49
	v_mad_i64_i32 v[48:49], s[2:3], v64, s14, v[112:113]
	v_lshl_add_u64 v[48:49], v[48:49], 0, s[30:31]
	v_lshl_add_u64 v[48:49], v[48:49], 0, s[38:39]
	v_lshl_add_u64 v[48:49], v[48:49], 0, v[190:191]
	global_store_dwordx4 v[48:49], v[56:59], off
	v_add_u32_e32 v48, 0x90, v140
	v_mov_b32_e32 v49, v204
	v_mul_f32_e32 v52, 0xbfb8aa3b, v49
	v_pk_mul_f32 v[54:55], v[44:45], v[52:53] op_sel_hi:[1,0]
	v_mul_f32_e32 v50, v49, v49
	v_exp_f32_e32 v54, v54
	v_exp_f32_e32 v55, v55
	s_nop 0
	v_pk_add_f32 v[54:55], v[54:55], 1.0 op_sel_hi:[1,0]
	s_nop 0
	v_rcp_f32_e32 v54, v54
	v_rcp_f32_e32 v55, v55
	s_nop 0
	v_pk_mul_f32 v[44:45], v[50:51], v[54:55] op_sel_hi:[0,1]
	v_pk_mul_f32 v[40:41], v[40:41], v[44:45]
	v_pk_mul_f32 v[44:45], v[46:47], v[52:53] op_sel_hi:[1,0]
	v_cvt_pk_bf16_f32 v40, v40, v41
	s_nop 0
	v_exp_f32_e32 v44, v44
	v_exp_f32_e32 v45, v45
	s_nop 0
	v_pk_add_f32 v[44:45], v[44:45], 1.0 op_sel_hi:[1,0]
	s_nop 0
	v_rcp_f32_e32 v44, v44
	v_rcp_f32_e32 v45, v45
	s_nop 0
	v_pk_mul_f32 v[44:45], v[50:51], v[44:45] op_sel_hi:[0,1]
	v_pk_mul_f32 v[42:43], v[42:43], v[44:45]
	s_nop 0
	v_cvt_pk_bf16_f32 v41, v42, v43
	v_pk_mul_f32 v[42:43], v[36:37], v[52:53] op_sel_hi:[1,0]
	s_nop 0
	v_exp_f32_e32 v42, v42
	v_exp_f32_e32 v43, v43
	s_nop 0
	v_pk_add_f32 v[42:43], v[42:43], 1.0 op_sel_hi:[1,0]
	s_nop 0
	v_rcp_f32_e32 v42, v42
; #define GAS __attribute__((address_space(1)))
;     __device__ __forceinline__ void operator()(const f32x4 (&acc)[2][2][4][2], const Unit& u, int wr, int wc, int fr, int fq) const {
;     ...
;             for (int m = 0; m < 4; ++m) {
;                 const int row = u.pm * BM + ai * HALF + wr * 64 + m * 16 + fr;
;                 const float rinv = row_rinv16(ssq, row);
;                 const float a = rinv * -1.4426950408889634f, r2 = rinv * rinv;
;                 u32x4 w;
;                 w.x = swiglu2(acc[ai][0][m][0][0], acc[ai][0][m][0][1], acc[ai][1][m][0][0], acc[ai][1][m][0][1], a, r2);
;                 w.y = swiglu2(acc[ai][0][m][0][2], acc[ai][0][m][0][3], acc[ai][1][m][0][2], acc[ai][1][m][0][3], a, r2);
;                 w.z = swiglu2(acc[ai][0][m][1][0], acc[ai][0][m][1][1], acc[ai][1][m][1][0], acc[ai][1][m][1][1], a, r2);
;                 w.w = swiglu2(acc[ai][0][m][1][2], acc[ai][0][m][1][3], acc[ai][1][m][1][2], acc[ai][1][m][1][3], a, r2);
;                 *(GAS u32x4*)(hid + (size_t)row * 2816 + u.pn * 128 + wc * 32 + 8 * fq) = w;
	v_rcp_f32_e32 v43, v43
	s_nop 0
	v_pk_mul_f32 v[36:37], v[50:51], v[42:43] op_sel_hi:[0,1]
	v_pk_mul_f32 v[32:33], v[32:33], v[36:37]
	s_nop 0
	v_cvt_pk_bf16_f32 v42, v32, v33
	v_pk_mul_f32 v[32:33], v[38:39], v[52:53] op_sel_hi:[1,0]
	s_nop 0
	v_exp_f32_e32 v32, v32
	v_exp_f32_e32 v33, v33
	s_nop 0
	v_pk_add_f32 v[32:33], v[32:33], 1.0 op_sel_hi:[1,0]
	s_nop 0
	v_rcp_f32_e32 v32, v32
	v_rcp_f32_e32 v33, v33
	s_nop 0
	v_pk_mul_f32 v[32:33], v[50:51], v[32:33] op_sel_hi:[0,1]
	v_pk_mul_f32 v[32:33], v[34:35], v[32:33]
	s_nop 0
	v_cvt_pk_bf16_f32 v43, v32, v33
	v_mad_i64_i32 v[32:33], s[2:3], v48, s14, v[112:113]
	v_lshl_add_u64 v[32:33], v[32:33], 0, s[30:31]
	v_lshl_add_u64 v[32:33], v[32:33], 0, s[38:39]
	v_lshl_add_u64 v[32:33], v[32:33], 0, v[190:191]
	global_store_dwordx4 v[32:33], v[40:43], off
	v_add_u32_e32 v32, 0xa0, v140
	v_mov_b32_e32 v33, v208
	v_mul_f32_e32 v36, 0xbfb8aa3b, v33
	v_pk_mul_f32 v[38:39], v[28:29], v[36:37] op_sel_hi:[1,0]
	v_mul_f32_e32 v34, v33, v33
	v_exp_f32_e32 v38, v38
	v_exp_f32_e32 v39, v39
	s_nop 0
	v_pk_add_f32 v[38:39], v[38:39], 1.0 op_sel_hi:[1,0]
	s_nop 0
	v_rcp_f32_e32 v38, v38
	v_rcp_f32_e32 v39, v39
	s_nop 0
	v_pk_mul_f32 v[28:29], v[34:35], v[38:39] op_sel_hi:[0,1]
	v_pk_mul_f32 v[24:25], v[24:25], v[28:29]
	v_pk_mul_f32 v[28:29], v[30:31], v[36:37] op_sel_hi:[1,0]
	v_cvt_pk_bf16_f32 v24, v24, v25
	s_nop 0
	v_exp_f32_e32 v28, v28
	v_exp_f32_e32 v29, v29
	s_nop 0
	v_pk_add_f32 v[28:29], v[28:29], 1.0 op_sel_hi:[1,0]
	s_nop 0
	v_rcp_f32_e32 v28, v28
	v_rcp_f32_e32 v29, v29
	s_nop 0
	v_pk_mul_f32 v[28:29], v[34:35], v[28:29] op_sel_hi:[0,1]
	v_pk_mul_f32 v[26:27], v[26:27], v[28:29]
	s_nop 0
	v_cvt_pk_bf16_f32 v25, v26, v27
	v_pk_mul_f32 v[26:27], v[20:21], v[36:37] op_sel_hi:[1,0]
	s_nop 0
	v_exp_f32_e32 v26, v26
	v_exp_f32_e32 v27, v27
	s_nop 0
	v_pk_add_f32 v[26:27], v[26:27], 1.0 op_sel_hi:[1,0]
	s_nop 0
	v_rcp_f32_e32 v26, v26
	v_rcp_f32_e32 v27, v27
	s_nop 0
	v_pk_mul_f32 v[20:21], v[34:35], v[26:27] op_sel_hi:[0,1]
	v_pk_mul_f32 v[16:17], v[16:17], v[20:21]
	s_nop 0
	v_cvt_pk_bf16_f32 v26, v16, v17
	v_pk_mul_f32 v[16:17], v[22:23], v[36:37] op_sel_hi:[1,0]
	s_nop 0
	v_exp_f32_e32 v16, v16
	v_exp_f32_e32 v17, v17
	s_nop 0
	v_pk_add_f32 v[16:17], v[16:17], 1.0 op_sel_hi:[1,0]
	s_nop 0
	v_rcp_f32_e32 v16, v16
	v_rcp_f32_e32 v17, v17
	s_nop 0
	v_pk_mul_f32 v[16:17], v[34:35], v[16:17] op_sel_hi:[0,1]
	v_pk_mul_f32 v[16:17], v[18:19], v[16:17]
	s_nop 0
	v_cvt_pk_bf16_f32 v27, v16, v17
	v_mad_i64_i32 v[16:17], s[2:3], v32, s14, v[112:113]
	v_lshl_add_u64 v[16:17], v[16:17], 0, s[30:31]
	v_lshl_add_u64 v[16:17], v[16:17], 0, s[38:39]
	v_lshl_add_u64 v[16:17], v[16:17], 0, v[190:191]
	global_store_dwordx4 v[16:17], v[24:27], off
	v_add_u32_e32 v16, 0xb0, v140
	v_mov_b32_e32 v17, v212
	v_mul_f32_e32 v20, 0xbfb8aa3b, v17
	v_pk_mul_f32 v[22:23], v[12:13], v[20:21] op_sel_hi:[1,0]
	v_mul_f32_e32 v18, v17, v17
	v_exp_f32_e32 v22, v22
	v_exp_f32_e32 v23, v23
	s_nop 0
	v_pk_add_f32 v[22:23], v[22:23], 1.0 op_sel_hi:[1,0]
	s_nop 0
	v_rcp_f32_e32 v22, v22
	v_rcp_f32_e32 v23, v23
	s_nop 0
	v_pk_mul_f32 v[12:13], v[18:19], v[22:23] op_sel_hi:[0,1]
	v_pk_mul_f32 v[8:9], v[8:9], v[12:13]
	v_pk_mul_f32 v[12:13], v[14:15], v[20:21] op_sel_hi:[1,0]
	v_cvt_pk_bf16_f32 v8, v8, v9
	s_nop 0
	v_exp_f32_e32 v12, v12
	v_exp_f32_e32 v13, v13
	s_nop 0
	v_pk_add_f32 v[12:13], v[12:13], 1.0 op_sel_hi:[1,0]
	s_nop 0
	v_rcp_f32_e32 v12, v12
	v_rcp_f32_e32 v13, v13
	s_nop 0
	v_pk_mul_f32 v[12:13], v[18:19], v[12:13] op_sel_hi:[0,1]
	v_pk_mul_f32 v[10:11], v[10:11], v[12:13]
	s_nop 0
	v_cvt_pk_bf16_f32 v9, v10, v11
	v_pk_mul_f32 v[10:11], v[4:5], v[20:21] op_sel_hi:[1,0]
	s_nop 0
	v_exp_f32_e32 v10, v10
	v_exp_f32_e32 v11, v11
	s_nop 0
	v_pk_add_f32 v[10:11], v[10:11], 1.0 op_sel_hi:[1,0]
	s_nop 0
	v_rcp_f32_e32 v10, v10
	v_rcp_f32_e32 v11, v11
	s_nop 0
	v_pk_mul_f32 v[4:5], v[18:19], v[10:11] op_sel_hi:[0,1]
	v_pk_mul_f32 v[0:1], v[0:1], v[4:5]
	s_nop 0
	v_cvt_pk_bf16_f32 v10, v0, v1
	v_pk_mul_f32 v[0:1], v[6:7], v[20:21] op_sel_hi:[1,0]
	s_nop 0
	v_exp_f32_e32 v0, v0
	v_exp_f32_e32 v1, v1
	s_nop 0
	v_pk_add_f32 v[0:1], v[0:1], 1.0 op_sel_hi:[1,0]
	s_nop 0
	v_rcp_f32_e32 v0, v0
	v_rcp_f32_e32 v1, v1
	s_nop 0
	v_pk_mul_f32 v[0:1], v[18:19], v[0:1] op_sel_hi:[0,1]
	v_pk_mul_f32 v[0:1], v[2:3], v[0:1]
	s_nop 0
	v_cvt_pk_bf16_f32 v11, v0, v1
	v_mad_i64_i32 v[0:1], s[2:3], v16, s14, v[112:113]
	v_lshl_add_u64 v[0:1], v[0:1], 0, s[30:31]
	v_lshl_add_u64 v[0:1], v[0:1], 0, s[38:39]
	v_lshl_add_u64 v[0:1], v[0:1], 0, v[190:191]
	s_mov_b64 s[2:3], -1
	global_store_dwordx4 v[0:1], v[8:11], off
	s_cbranch_vccnz .LBB0_1381
	v_mov_b32_e32 v0, v191
	s_andn2_b64 vcc, exec, s[4:5]
	s_cbranch_vccnz .LBB0_1380
	s_barrier
	s_branch .LBB0_1380

; __global__ void __launch_bounds__(NTHREADS, 2) fwd_megakernel(Args a) {
	.amdhsa_kernel _Z14fwd_megakernel4Args
		.amdhsa_group_segment_fixed_size 0
		.amdhsa_private_segment_fixed_size 0
		.amdhsa_kernarg_size 464
		.amdhsa_user_sgpr_count 2
		.amdhsa_user_sgpr_dispatch_ptr 0
		.amdhsa_user_sgpr_queue_ptr 0
		.amdhsa_user_sgpr_kernarg_segment_ptr 1
		.amdhsa_user_sgpr_dispatch_id 0
		.amdhsa_user_sgpr_kernarg_preload_length 0
		.amdhsa_user_sgpr_kernarg_preload_offset 0
		.amdhsa_user_sgpr_private_segment_size 0
		.amdhsa_uses_dynamic_stack 0
		.amdhsa_enable_private_segment 0
		.amdhsa_system_sgpr_workgroup_id_x 1
		.amdhsa_system_sgpr_workgroup_id_y 0
		.amdhsa_system_sgpr_workgroup_id_z 0
		.amdhsa_system_sgpr_workgroup_info 0
		.amdhsa_system_vgpr_workitem_id 2
		.amdhsa_next_free_vgpr 256
		.amdhsa_next_free_sgpr 102
		.amdhsa_accum_offset 256
		.amdhsa_reserve_vcc 1
		.amdhsa_float_round_mode_32 0
		.amdhsa_float_round_mode_16_64 0
		.amdhsa_float_denorm_mode_32 3
		.amdhsa_float_denorm_mode_16_64 3
		.amdhsa_dx10_clamp 1
		.amdhsa_ieee_mode 1
		.amdhsa_fp16_overflow 0
		.amdhsa_tg_split 0
		.amdhsa_exception_fp_ieee_invalid_op 0
		.amdhsa_exception_fp_denorm_src 0
		.amdhsa_exception_fp_ieee_div_zero 0
		.amdhsa_exception_fp_ieee_overflow 0
		.amdhsa_exception_fp_ieee_underflow 0
		.amdhsa_exception_fp_ieee_inexact 0
		.amdhsa_exception_int_div_zero 0
	.end_amdhsa_kernel

; __global__ void __launch_bounds__(NTHREADS, 2) fwd_megakernel(Args a) {
amdhsa.kernels:
  - .agpr_count:     0
    .args:
      - .offset:         0
        .size:           208
        .value_kind:     by_value
      - .offset:         208
        .size:           4
        .value_kind:     hidden_block_count_x
      - .offset:         212
        .size:           4
        .value_kind:     hidden_block_count_y
      - .offset:         216
        .size:           4
        .value_kind:     hidden_block_count_z
      - .offset:         220
        .size:           2
        .value_kind:     hidden_group_size_x
      - .offset:         222
        .size:           2
        .value_kind:     hidden_group_size_y
      - .offset:         224
        .size:           2
        .value_kind:     hidden_group_size_z
      - .offset:         226
        .size:           2
        .value_kind:     hidden_remainder_x
      - .offset:         228
        .size:           2
        .value_kind:     hidden_remainder_y
      - .offset:         230
        .size:           2
        .value_kind:     hidden_remainder_z
      - .offset:         248
        .size:           8
        .value_kind:     hidden_global_offset_x
      - .offset:         256
        .size:           8
        .value_kind:     hidden_global_offset_y
      - .offset:         264
        .size:           8
        .value_kind:     hidden_global_offset_z
      - .offset:         272
        .size:           2
        .value_kind:     hidden_grid_dims
      - .offset:         296
        .size:           8
        .value_kind:     hidden_multigrid_sync_arg
      - .offset:         328
        .size:           4
        .value_kind:     hidden_dynamic_lds_size
    .group_segment_fixed_size: 0
    .kernarg_segment_align: 8
    .kernarg_segment_size: 464
    .language:       OpenCL C
    .language_version:
      - 2
      - 0
    .max_flat_workgroup_size: 512
    .name:           _Z14fwd_megakernel4Args
    .private_segment_fixed_size: 0
    .sgpr_count:     108
    .sgpr_spill_count: 192
    .symbol:         _Z14fwd_megakernel4Args.kd
    .uniform_work_group_size: 1
    .uses_dynamic_stack: false
    .vgpr_count:     256
    .vgpr_spill_count: 0
    .wavefront_size: 64
